# retention V tile staged by LDS-DMA (512B rows, 32B-slot XOR swizzle, 8 read bases), loop-invariant DMA offsets hoisted
# speedup vs baseline: 1.0054x; 1.0054x over previous
.LBB0_860:
	s_mul_i32 s16, s16, 0x8800
	v_add_u32_e32 v8, s16, v173
	v_xor_b32_e32 v210, 0x20, v8
	v_xor_b32_e32 v211, 0x40, v8
	v_xor_b32_e32 v212, 0x60, v8
	v_xor_b32_e32 v213, 0x80, v8
	v_xor_b32_e32 v214, 0xa0, v8
	v_xor_b32_e32 v215, 0xc0, v8
	v_xor_b32_e32 v216, 0xe0, v8
	ds_read_b64_tr_b16 v[74:75], v8
	ds_read_b64_tr_b16 v[76:77], v8 offset:8192
	ds_read_b64_tr_b16 v[80:81], v210 offset:8192
	ds_read_b64_tr_b16 v[78:79], v210
	ds_read_b64_tr_b16 v[82:83], v211
	ds_read_b64_tr_b16 v[86:87], v212
	ds_read_b64_tr_b16 v[84:85], v211 offset:8192
	ds_read_b64_tr_b16 v[88:89], v212 offset:8192
	s_waitcnt lgkmcnt(6)
	v_mfma_f32_16x16x32_bf16 v[70:73], v[74:77], v[0:3], v[70:73]
	v_cvt_pk_bf16_f32 v6, v90, v91
	v_cvt_pk_bf16_f32 v7, v92, v93
	s_waitcnt lgkmcnt(4)
	v_mfma_f32_16x16x32_bf16 v[66:69], v[78:81], v[0:3], v[66:69]
	ds_read_b64_tr_b16 v[74:75], v213
	ds_read_b64_tr_b16 v[78:79], v214
	ds_read_b64_tr_b16 v[90:91], v215
	ds_read_b64_tr_b16 v[94:95], v216
	ds_read_b64_tr_b16 v[76:77], v213 offset:8192
	ds_read_b64_tr_b16 v[80:81], v214 offset:8192
	ds_read_b64_tr_b16 v[92:93], v215 offset:8192
	ds_read_b64_tr_b16 v[96:97], v216 offset:8192
	s_waitcnt lgkmcnt(9)
	v_mfma_f32_16x16x32_bf16 v[62:65], v[82:85], v[0:3], v[62:65]
	s_waitcnt lgkmcnt(8)
	v_mfma_f32_16x16x32_bf16 v[58:61], v[86:89], v[0:3], v[58:61]
	s_waitcnt lgkmcnt(3)
	v_mfma_f32_16x16x32_bf16 v[54:57], v[74:77], v[0:3], v[54:57]
	s_waitcnt lgkmcnt(2)
	v_mfma_f32_16x16x32_bf16 v[50:53], v[78:81], v[0:3], v[50:53]
	ds_read_b64_tr_b16 v[74:75], v8 offset:256
	ds_read_b64_tr_b16 v[78:79], v210 offset:256
	ds_read_b64_tr_b16 v[82:83], v211 offset:256
	ds_read_b64_tr_b16 v[86:87], v212 offset:256
	ds_read_b64_tr_b16 v[76:77], v8 offset:8448
	ds_read_b64_tr_b16 v[80:81], v210 offset:8448
	ds_read_b64_tr_b16 v[84:85], v211 offset:8448
	ds_read_b64_tr_b16 v[88:89], v212 offset:8448
	s_waitcnt lgkmcnt(9)
	v_mfma_f32_16x16x32_bf16 v[46:49], v[90:93], v[0:3], v[46:49]
	s_waitcnt lgkmcnt(8)
	v_mfma_f32_16x16x32_bf16 v[42:45], v[94:97], v[0:3], v[42:45]
	s_waitcnt lgkmcnt(3)
	v_mfma_f32_16x16x32_bf16 v[38:41], v[74:77], v[0:3], v[38:41]
	s_waitcnt lgkmcnt(2)
	v_mfma_f32_16x16x32_bf16 v[34:37], v[78:81], v[0:3], v[34:37]
	ds_read_b64_tr_b16 v[74:75], v213 offset:256
	ds_read_b64_tr_b16 v[78:79], v214 offset:256
	ds_read_b64_tr_b16 v[90:91], v215 offset:256
	ds_read_b64_tr_b16 v[94:95], v216 offset:256
	ds_read_b64_tr_b16 v[76:77], v213 offset:8448
	ds_read_b64_tr_b16 v[80:81], v214 offset:8448
	ds_read_b64_tr_b16 v[92:93], v215 offset:8448
	ds_read_b64_tr_b16 v[96:97], v216 offset:8448
	s_waitcnt lgkmcnt(9)
	v_mfma_f32_16x16x32_bf16 v[30:33], v[82:85], v[0:3], v[30:33]
	s_waitcnt lgkmcnt(8)
	v_mfma_f32_16x16x32_bf16 v[26:29], v[86:89], v[0:3], v[26:29]
	s_waitcnt lgkmcnt(3)
	v_mfma_f32_16x16x32_bf16 v[22:25], v[74:77], v[0:3], v[22:25]
	s_waitcnt lgkmcnt(2)
	v_mfma_f32_16x16x32_bf16 v[18:21], v[78:81], v[0:3], v[18:21]
	ds_read_b64_tr_b16 v[74:75], v8 offset:16384
	ds_read_b64_tr_b16 v[78:79], v210 offset:16384
	ds_read_b64_tr_b16 v[82:83], v211 offset:16384
	ds_read_b64_tr_b16 v[86:87], v212 offset:16384
	ds_read_b64_tr_b16 v[76:77], v8 offset:24576
	ds_read_b64_tr_b16 v[80:81], v210 offset:24576
	ds_read_b64_tr_b16 v[84:85], v211 offset:24576
	ds_read_b64_tr_b16 v[88:89], v212 offset:24576
	s_waitcnt lgkmcnt(9)
	v_mfma_f32_16x16x32_bf16 v[14:17], v[90:93], v[0:3], v[14:17]
	s_waitcnt lgkmcnt(8)
	v_mfma_f32_16x16x32_bf16 v[0:3], v[94:97], v[0:3], v[10:13]
	s_waitcnt lgkmcnt(3)
	v_mfma_f32_16x16x32_bf16 v[70:73], v[74:77], v[4:7], v[70:73]
	s_waitcnt lgkmcnt(2)
	v_mfma_f32_16x16x32_bf16 v[66:69], v[78:81], v[4:7], v[66:69]
	ds_read_b64_tr_b16 v[10:11], v213 offset:16384
	ds_read_b64_tr_b16 v[74:75], v214 offset:16384
	ds_read_b64_tr_b16 v[78:79], v215 offset:16384
	ds_read_b64_tr_b16 v[90:91], v216 offset:16384
	ds_read_b64_tr_b16 v[12:13], v213 offset:24576
	ds_read_b64_tr_b16 v[76:77], v214 offset:24576
	ds_read_b64_tr_b16 v[80:81], v215 offset:24576
	ds_read_b64_tr_b16 v[92:93], v216 offset:24576
	s_waitcnt lgkmcnt(9)
	v_mfma_f32_16x16x32_bf16 v[62:65], v[82:85], v[4:7], v[62:65]
	s_waitcnt lgkmcnt(8)
	v_mfma_f32_16x16x32_bf16 v[58:61], v[86:89], v[4:7], v[58:61]
	s_waitcnt lgkmcnt(3)
	v_mfma_f32_16x16x32_bf16 v[54:57], v[10:13], v[4:7], v[54:57]
	s_waitcnt lgkmcnt(2)
	v_mfma_f32_16x16x32_bf16 v[50:53], v[74:77], v[4:7], v[50:53]
	ds_read_b64_tr_b16 v[10:11], v8 offset:16640
	ds_read_b64_tr_b16 v[74:75], v210 offset:16640
	ds_read_b64_tr_b16 v[82:83], v211 offset:16640
	ds_read_b64_tr_b16 v[86:87], v212 offset:16640
	ds_read_b64_tr_b16 v[12:13], v8 offset:24832
	ds_read_b64_tr_b16 v[76:77], v210 offset:24832
	ds_read_b64_tr_b16 v[84:85], v211 offset:24832
	ds_read_b64_tr_b16 v[88:89], v212 offset:24832
	s_waitcnt lgkmcnt(9)
	v_mfma_f32_16x16x32_bf16 v[46:49], v[78:81], v[4:7], v[46:49]
	s_waitcnt lgkmcnt(8)
	v_mfma_f32_16x16x32_bf16 v[42:45], v[90:93], v[4:7], v[42:45]
	s_waitcnt lgkmcnt(3)
	v_mfma_f32_16x16x32_bf16 v[38:41], v[10:13], v[4:7], v[38:41]
	s_waitcnt lgkmcnt(2)
	v_mfma_f32_16x16x32_bf16 v[34:37], v[74:77], v[4:7], v[34:37]
	ds_read_b64_tr_b16 v[10:11], v213 offset:16640
	ds_read_b64_tr_b16 v[74:75], v214 offset:16640
	ds_read_b64_tr_b16 v[78:79], v215 offset:16640
	ds_read_b64_tr_b16 v[90:91], v216 offset:16640
	ds_read_b64_tr_b16 v[12:13], v213 offset:24832
	ds_read_b64_tr_b16 v[76:77], v214 offset:24832
	ds_read_b64_tr_b16 v[80:81], v215 offset:24832
	ds_read_b64_tr_b16 v[92:93], v216 offset:24832
	s_waitcnt lgkmcnt(9)
	v_mfma_f32_16x16x32_bf16 v[30:33], v[82:85], v[4:7], v[30:33]
	s_waitcnt lgkmcnt(8)
	v_mfma_f32_16x16x32_bf16 v[26:29], v[86:89], v[4:7], v[26:29]
	s_waitcnt lgkmcnt(3)
	v_mfma_f32_16x16x32_bf16 v[22:25], v[10:13], v[4:7], v[22:25]
	s_waitcnt lgkmcnt(2)
	v_mfma_f32_16x16x32_bf16 v[18:21], v[74:77], v[4:7], v[18:21]
	s_waitcnt lgkmcnt(1)
	v_mfma_f32_16x16x32_bf16 v[14:17], v[78:81], v[4:7], v[14:17]
	s_waitcnt lgkmcnt(0)
	v_mfma_f32_16x16x32_bf16 v[10:13], v[90:93], v[4:7], v[0:3]

.LBB0_862:
	s_xor_b64 s[46:47], s[4:5], -1
	s_and_b64 s[4:5], s[4:5], exec
	v_mov_b32_e32 v20, v170
	s_cselect_b32 s9, s7, s8
	v_readfirstlane_b32 s4, v20
	s_ashr_i32 s4, s4, 2
	s_and_b32 s4, s4, -16
	v_and_b32_e32 v21, 15, v20
	s_add_i32 s4, s4, s9
	v_or_b32_e32 v172, s4, v21
	v_ashrrev_i32_e32 v173, 31, v172
	v_bfe_u32 v22, v20, 4, 2
	s_waitcnt lgkmcnt(0)
	v_lshlrev_b64 v[0:1], 14, v[172:173]
	v_lshl_add_u64 v[0:1], s[22:23], 0, v[0:1]
	v_lshlrev_b32_e32 v8, 4, v22
	v_lshl_add_u64 v[0:1], v[0:1], 0, v[8:9]
	v_mov_b32_e32 v16, v170
	global_load_dwordx4 v[102:105], v[0:1], off
	global_load_dwordx4 v[98:101], v[0:1], off offset:64
	global_load_dwordx4 v[94:97], v[0:1], off offset:128
	global_load_dwordx4 v[90:93], v[0:1], off offset:192
	global_load_dwordx4 v[86:89], v[0:1], off offset:256
	global_load_dwordx4 v[82:85], v[0:1], off offset:320
	global_load_dwordx4 v[78:81], v[0:1], off offset:384
	global_load_dwordx4 v[74:77], v[0:1], off offset:448
	v_mov_b32_e32 v23, v170
	v_lshlrev_b32_e32 v0, 4, v16
	v_and_b32_e32 v8, 0x1f0, v0
	v_lshl_add_u64 v[14:15], s[24:25], 0, v[8:9]
	v_lshrrev_b32_e32 v8, 5, v16
	v_lshlrev_b64 v[0:1], 14, v[8:9]
	v_lshl_add_u64 v[0:1], v[14:15], 0, v[0:1]
	v_add_u32_e32 v4, 0x200, v16
	global_load_dwordx4 v[0:3], v[0:1], off
	v_lshrrev_b32_e32 v8, 5, v4
	v_lshlrev_b64 v[4:5], 14, v[8:9]
	v_lshl_add_u64 v[4:5], v[14:15], 0, v[4:5]
	v_add_u32_e32 v8, 0x400, v16
	global_load_dwordx4 v[4:7], v[4:5], off
	v_lshrrev_b32_e32 v8, 5, v8
	v_lshlrev_b64 v[10:11], 14, v[8:9]
	v_lshl_add_u64 v[10:11], v[14:15], 0, v[10:11]
	v_add_u32_e32 v8, 0x600, v16
	global_load_dwordx4 v[10:13], v[10:11], off
	v_lshrrev_b32_e32 v8, 5, v8
	v_lshlrev_b64 v[16:17], 14, v[8:9]
	v_lshl_add_u64 v[14:15], v[14:15], 0, v[16:17]
	global_load_dwordx4 v[14:17], v[14:15], off
	v_lshlrev_b32_e32 v194, 2, v22
	v_lshlrev_b32_e32 v8, 4, v23
	v_and_b32_e32 v8, 0x1f0, v8
	v_lshrrev_b32_e32 v246, 1, v23
	v_and_b32_e32 v246, 0xf0, v246
	v_xor_b32_e32 v8, v8, v246
	v_add_u32_e32 v8, 0, v8
	v_lshrrev_b32_e32 v18, 5, v23
	v_mad_u64_u32 v[18:19], s[16:17], v18, s96, v[8:9]
	s_add_i32 s5, s9, 0x80
	v_readfirstlane_b32 s40, v179
	v_readfirstlane_b32 s44, v180
	v_readfirstlane_b32 s41, v181
	v_readfirstlane_b32 s37, v190
	v_readfirstlane_b32 s42, v191
	v_readfirstlane_b32 s36, v192
	v_readfirstlane_b32 s43, v193
	v_mov_b32_e32 v171, v172
	s_mov_b32 s45, 0
	s_mov_b32 s48, 0
	s_waitcnt vmcnt(3)
	ds_write_b128 v18, v[0:3]
	v_add_u32_e32 v0, 0x200, v23
	v_lshrrev_b32_e32 v0, 5, v0
	v_mad_u64_u32 v[0:1], s[16:17], v0, s96, v[8:9]
	s_waitcnt vmcnt(2)
	ds_write_b128 v0, v[4:7]
	v_add_u32_e32 v0, 0x400, v23
	v_lshrrev_b32_e32 v0, 5, v0
	v_mad_u64_u32 v[0:1], s[16:17], v0, s96, v[8:9]
	s_waitcnt vmcnt(1)
	ds_write_b128 v0, v[10:13]
	v_add_u32_e32 v0, 0x600, v23
	v_lshrrev_b32_e32 v0, 5, v0
	v_mad_u64_u32 v[0:1], s[16:17], v0, s96, v[8:9]
	s_waitcnt vmcnt(0)
	ds_write_b128 v0, v[14:17]
	v_mov_b32_e32 v16, v170
	v_mov_b32_e32 v23, v170
	v_lshlrev_b32_e32 v0, 4, v16
	v_and_b32_e32 v8, 0x1f0, v0
	v_lshl_add_u64 v[14:15], s[26:27], 0, v[8:9]
	v_lshrrev_b32_e32 v8, 5, v16
	v_lshlrev_b64 v[0:1], 14, v[8:9]
	v_lshl_add_u64 v[0:1], v[14:15], 0, v[0:1]
	v_add_u32_e32 v4, 0x200, v16
	global_load_dwordx4 v[0:3], v[0:1], off
	v_lshrrev_b32_e32 v8, 5, v4
	v_lshlrev_b64 v[4:5], 14, v[8:9]
	v_lshl_add_u64 v[4:5], v[14:15], 0, v[4:5]
	v_add_u32_e32 v8, 0x400, v16
	global_load_dwordx4 v[4:7], v[4:5], off
	v_lshrrev_b32_e32 v8, 5, v8
	v_lshlrev_b64 v[10:11], 14, v[8:9]
	v_lshl_add_u64 v[10:11], v[14:15], 0, v[10:11]
	v_add_u32_e32 v8, 0x600, v16
	global_load_dwordx4 v[10:13], v[10:11], off
	v_lshrrev_b32_e32 v8, 5, v8
	v_lshlrev_b64 v[16:17], 14, v[8:9]
	v_lshl_add_u64 v[14:15], v[14:15], 0, v[16:17]
	global_load_dwordx4 v[14:17], v[14:15], off
	s_nop 0
	v_lshlrev_b32_e32 v8, 4, v23
	v_and_b32_e32 v8, 0x1f0, v8
	v_lshrrev_b32_e32 v246, 5, v23
	v_and_b32_e32 v246, 7, v246
	v_lshlrev_b32_e32 v246, 5, v246
	v_xor_b32_e32 v8, v8, v246
	v_add_u32_e32 v8, s97, v8
	v_lshrrev_b32_e32 v18, 5, v23
	v_mad_u64_u32 v[18:19], s[16:17], v18, s96, v[8:9]
	s_waitcnt vmcnt(3)
	ds_write_b128 v18, v[0:3]
	v_add_u32_e32 v0, 0x200, v23
	v_lshrrev_b32_e32 v0, 5, v0
	v_mad_u64_u32 v[0:1], s[16:17], v0, s96, v[8:9]
	s_waitcnt vmcnt(2)
	ds_write_b128 v0, v[4:7]
	v_add_u32_e32 v0, 0x400, v23
	v_lshrrev_b32_e32 v0, 5, v0
	v_mad_u64_u32 v[0:1], s[16:17], v0, s96, v[8:9]
	s_waitcnt vmcnt(1)
	ds_write_b128 v0, v[10:13]
	v_add_u32_e32 v0, 0x600, v23
	v_lshrrev_b32_e32 v0, 5, v0
	v_mad_u64_u32 v[0:1], s[16:17], v0, s96, v[8:9]
	s_waitcnt vmcnt(0)
	ds_write_b128 v0, v[14:17]
	v_lshlrev_b32_e32 v0, 9, v21
	v_and_b32_e32 v1, 48, v20
	v_lshlrev_b32_e32 v246, 4, v21
	v_xor_b32_e32 v1, v1, v246
	v_add3_u32 v195, 0, v0, v1
	v_bfe_u32 v0, v20, 2, 2
	v_or_b32_e32 v0, v194, v0
	v_lshlrev_b32_e32 v1, 3, v20
	v_and_b32_e32 v246, 7, v0
	v_lshlrev_b32_e32 v246, 5, v246
	v_lshl_or_b32 v0, v0, 9, v246
	v_and_b32_e32 v1, 24, v1
	v_mov_b32_e32 v10, v9
	v_mov_b32_e32 v11, v9
	v_add3_u32 v173, s97, v0, v1
	v_add_u32_e32 v0, s4, v21
	v_mov_b32_e32 v8, v9
	v_mov_b64_e32 v[44:45], v[10:11]
	v_mov_b64_e32 v[48:49], v[10:11]
	v_mov_b64_e32 v[52:53], v[10:11]
	v_mov_b64_e32 v[56:57], v[10:11]
	v_mov_b64_e32 v[60:61], v[10:11]
	v_mov_b64_e32 v[64:65], v[10:11]
	v_mov_b64_e32 v[68:69], v[10:11]
	v_mov_b64_e32 v[72:73], v[10:11]
	v_mov_b64_e32 v[40:41], v[10:11]
	v_mov_b64_e32 v[36:37], v[10:11]
	v_mov_b64_e32 v[32:33], v[10:11]
	v_mov_b64_e32 v[28:29], v[10:11]
	v_mov_b64_e32 v[24:25], v[10:11]
	v_mov_b64_e32 v[20:21], v[10:11]
	v_mov_b64_e32 v[16:17], v[10:11]
	s_lshr_b32 s17, s5, 6
	v_mov_b64_e32 v[42:43], v[8:9]
	v_mov_b64_e32 v[46:47], v[8:9]
	v_mov_b64_e32 v[50:51], v[8:9]
	v_mov_b64_e32 v[54:55], v[8:9]
	v_mov_b64_e32 v[58:59], v[8:9]
	v_mov_b64_e32 v[62:63], v[8:9]
	v_mov_b64_e32 v[66:67], v[8:9]
	v_mov_b64_e32 v[70:71], v[8:9]
	v_mov_b64_e32 v[38:39], v[8:9]
	v_mov_b64_e32 v[34:35], v[8:9]
	v_mov_b64_e32 v[30:31], v[8:9]
	v_mov_b64_e32 v[26:27], v[8:9]
	v_mov_b64_e32 v[22:23], v[8:9]
	v_mov_b64_e32 v[18:19], v[8:9]
	v_mov_b64_e32 v[14:15], v[8:9]
	v_mov_b64_e32 v[12:13], v[10:11]
	s_or_b32 s16, s4, 15
	s_add_i32 s17, s17, -1
	v_sub_u32_e32 v196, v0, v194
	v_mov_b64_e32 v[10:11], v[8:9]
	v_lshrrev_b32_e32 v106, 5, v170
	v_and_b32_e32 v107, 31, v170
	v_and_b32_e32 v108, 15, v106
	v_xor_b32_e32 v108, v107, v108
	v_and_b32_e32 v109, 7, v106
	v_lshlrev_b32_e32 v109, 1, v109
	v_xor_b32_e32 v107, v107, v109
	v_lshlrev_b32_e32 v109, 14, v106
	v_lshl_or_b32 v106, v108, 4, v109
	v_lshl_or_b32 v107, v107, 4, v109
	s_waitcnt lgkmcnt(0)
	s_barrier
	s_branch .LBB0_865
.LBB0_863:
	s_mul_i32 s4, s49, 0x8800
	v_add_u32_e32 v8, s4, v173
	v_xor_b32_e32 v210, 0x20, v8
	v_xor_b32_e32 v211, 0x40, v8
	v_xor_b32_e32 v212, 0x60, v8
	v_xor_b32_e32 v213, 0x80, v8
	v_xor_b32_e32 v214, 0xa0, v8
	v_xor_b32_e32 v215, 0xc0, v8
	v_xor_b32_e32 v216, 0xe0, v8
	v_cvt_pk_bf16_f32 v6, v174, v175
	v_cvt_pk_bf16_f32 v7, v176, v177
	s_nop 1
	ds_read_b64_tr_b16 v[138:139], v8
	ds_read_b64_tr_b16 v[140:141], v8 offset:8192
	ds_read_b64_tr_b16 v[142:143], v210
	ds_read_b64_tr_b16 v[144:145], v210 offset:8192
	ds_read_b64_tr_b16 v[146:147], v211
	ds_read_b64_tr_b16 v[148:149], v211 offset:8192
	ds_read_b64_tr_b16 v[150:151], v212
	ds_read_b64_tr_b16 v[152:153], v212 offset:8192
	ds_read_b64_tr_b16 v[198:199], v213
	ds_read_b64_tr_b16 v[200:201], v213 offset:8192
	ds_read_b64_tr_b16 v[202:203], v214
	ds_read_b64_tr_b16 v[204:205], v214 offset:8192
	ds_read_b64_tr_b16 v[206:207], v215
	ds_read_b64_tr_b16 v[208:209], v215 offset:8192
	s_waitcnt lgkmcnt(12)
	v_mfma_f32_16x16x32_bf16 v[70:73], v[138:141], v[0:3], v[70:73]
	ds_read_b64_tr_b16 v[138:139], v216
	ds_read_b64_tr_b16 v[140:141], v216 offset:8192
	s_waitcnt lgkmcnt(12)
	v_mfma_f32_16x16x32_bf16 v[66:69], v[142:145], v[0:3], v[66:69]
	ds_read_b64_tr_b16 v[142:143], v8 offset:256
	ds_read_b64_tr_b16 v[144:145], v8 offset:8448
	s_waitcnt lgkmcnt(12)
	v_mfma_f32_16x16x32_bf16 v[62:65], v[146:149], v[0:3], v[62:65]
	ds_read_b64_tr_b16 v[146:147], v210 offset:256
	ds_read_b64_tr_b16 v[148:149], v210 offset:8448
	s_waitcnt lgkmcnt(12)
	v_mfma_f32_16x16x32_bf16 v[58:61], v[150:153], v[0:3], v[58:61]
	ds_read_b64_tr_b16 v[150:151], v211 offset:256
	ds_read_b64_tr_b16 v[152:153], v211 offset:8448
	s_waitcnt lgkmcnt(12)
	v_mfma_f32_16x16x32_bf16 v[54:57], v[198:201], v[0:3], v[54:57]
	ds_read_b64_tr_b16 v[198:199], v212 offset:256
	ds_read_b64_tr_b16 v[200:201], v212 offset:8448
	s_waitcnt lgkmcnt(12)
	v_mfma_f32_16x16x32_bf16 v[50:53], v[202:205], v[0:3], v[50:53]
	ds_read_b64_tr_b16 v[202:203], v213 offset:256
	ds_read_b64_tr_b16 v[204:205], v213 offset:8448
	s_waitcnt lgkmcnt(12)
	v_mfma_f32_16x16x32_bf16 v[46:49], v[206:209], v[0:3], v[46:49]
	ds_read_b64_tr_b16 v[206:207], v214 offset:256
	ds_read_b64_tr_b16 v[208:209], v214 offset:8448
	s_waitcnt lgkmcnt(12)
	v_mfma_f32_16x16x32_bf16 v[42:45], v[138:141], v[0:3], v[42:45]
	ds_read_b64_tr_b16 v[138:139], v215 offset:256
	ds_read_b64_tr_b16 v[140:141], v215 offset:8448
	s_waitcnt lgkmcnt(12)
	v_mfma_f32_16x16x32_bf16 v[38:41], v[142:145], v[0:3], v[38:41]
	ds_read_b64_tr_b16 v[142:143], v216 offset:256
	ds_read_b64_tr_b16 v[144:145], v216 offset:8448
	s_waitcnt lgkmcnt(12)
	v_mfma_f32_16x16x32_bf16 v[34:37], v[146:149], v[0:3], v[34:37]
	ds_read_b64_tr_b16 v[146:147], v8 offset:16384
	ds_read_b64_tr_b16 v[148:149], v8 offset:24576
	s_waitcnt lgkmcnt(12)
	v_mfma_f32_16x16x32_bf16 v[30:33], v[150:153], v[0:3], v[30:33]
	ds_read_b64_tr_b16 v[150:151], v210 offset:16384
	ds_read_b64_tr_b16 v[152:153], v210 offset:24576
	s_waitcnt lgkmcnt(12)
	v_mfma_f32_16x16x32_bf16 v[26:29], v[198:201], v[0:3], v[26:29]
	ds_read_b64_tr_b16 v[198:199], v211 offset:16384
	ds_read_b64_tr_b16 v[200:201], v211 offset:24576
	s_waitcnt lgkmcnt(12)
	v_mfma_f32_16x16x32_bf16 v[22:25], v[202:205], v[0:3], v[22:25]
	ds_read_b64_tr_b16 v[202:203], v212 offset:16384
	ds_read_b64_tr_b16 v[204:205], v212 offset:24576
	s_waitcnt lgkmcnt(12)
	v_mfma_f32_16x16x32_bf16 v[18:21], v[206:209], v[0:3], v[18:21]
	ds_read_b64_tr_b16 v[206:207], v213 offset:16384
	ds_read_b64_tr_b16 v[208:209], v213 offset:24576
	s_waitcnt lgkmcnt(12)
	v_mfma_f32_16x16x32_bf16 v[14:17], v[138:141], v[0:3], v[14:17]
	ds_read_b64_tr_b16 v[138:139], v214 offset:16384
	ds_read_b64_tr_b16 v[140:141], v214 offset:24576
	s_waitcnt lgkmcnt(12)
	v_mfma_f32_16x16x32_bf16 v[10:13], v[142:145], v[0:3], v[10:13]
	ds_read_b64_tr_b16 v[142:143], v215 offset:16384
	ds_read_b64_tr_b16 v[144:145], v215 offset:24576
	s_waitcnt lgkmcnt(12)
	v_mfma_f32_16x16x32_bf16 v[70:73], v[146:149], v[4:7], v[70:73]
	ds_read_b64_tr_b16 v[146:147], v216 offset:16384
	ds_read_b64_tr_b16 v[148:149], v216 offset:24576
	s_waitcnt lgkmcnt(12)
	v_mfma_f32_16x16x32_bf16 v[66:69], v[150:153], v[4:7], v[66:69]
	ds_read_b64_tr_b16 v[150:151], v8 offset:16640
	ds_read_b64_tr_b16 v[152:153], v8 offset:24832
	s_waitcnt lgkmcnt(12)
	v_mfma_f32_16x16x32_bf16 v[62:65], v[198:201], v[4:7], v[62:65]
	ds_read_b64_tr_b16 v[198:199], v210 offset:16640
	ds_read_b64_tr_b16 v[200:201], v210 offset:24832
	s_waitcnt lgkmcnt(12)
	v_mfma_f32_16x16x32_bf16 v[58:61], v[202:205], v[4:7], v[58:61]
	ds_read_b64_tr_b16 v[202:203], v211 offset:16640
	ds_read_b64_tr_b16 v[204:205], v211 offset:24832
	s_waitcnt lgkmcnt(12)
	v_mfma_f32_16x16x32_bf16 v[54:57], v[206:209], v[4:7], v[54:57]
	ds_read_b64_tr_b16 v[206:207], v212 offset:16640
	ds_read_b64_tr_b16 v[208:209], v212 offset:24832
	s_waitcnt lgkmcnt(12)
	v_mfma_f32_16x16x32_bf16 v[50:53], v[138:141], v[4:7], v[50:53]
	ds_read_b64_tr_b16 v[138:139], v213 offset:16640
	ds_read_b64_tr_b16 v[140:141], v213 offset:24832
	s_waitcnt lgkmcnt(12)
	v_mfma_f32_16x16x32_bf16 v[46:49], v[142:145], v[4:7], v[46:49]
	ds_read_b64_tr_b16 v[142:143], v214 offset:16640
	ds_read_b64_tr_b16 v[144:145], v214 offset:24832
	s_waitcnt lgkmcnt(12)
	v_mfma_f32_16x16x32_bf16 v[42:45], v[146:149], v[4:7], v[42:45]
	ds_read_b64_tr_b16 v[146:147], v215 offset:16640
	ds_read_b64_tr_b16 v[148:149], v215 offset:24832
	s_waitcnt lgkmcnt(12)
	v_mfma_f32_16x16x32_bf16 v[38:41], v[150:153], v[4:7], v[38:41]
	ds_read_b64_tr_b16 v[150:151], v216 offset:16640
	ds_read_b64_tr_b16 v[152:153], v216 offset:24832
	s_waitcnt lgkmcnt(12)
	v_mfma_f32_16x16x32_bf16 v[34:37], v[198:201], v[4:7], v[34:37]
	s_waitcnt lgkmcnt(10)
	v_mfma_f32_16x16x32_bf16 v[30:33], v[202:205], v[4:7], v[30:33]
	s_waitcnt lgkmcnt(8)
	v_mfma_f32_16x16x32_bf16 v[26:29], v[206:209], v[4:7], v[26:29]
	s_waitcnt lgkmcnt(6)
	v_mfma_f32_16x16x32_bf16 v[22:25], v[138:141], v[4:7], v[22:25]
	s_waitcnt lgkmcnt(4)
	v_mfma_f32_16x16x32_bf16 v[18:21], v[142:145], v[4:7], v[18:21]
	s_waitcnt lgkmcnt(2)
	v_mfma_f32_16x16x32_bf16 v[14:17], v[146:149], v[4:7], v[14:17]
	s_waitcnt lgkmcnt(0)
	v_mfma_f32_16x16x32_bf16 v[10:13], v[150:153], v[4:7], v[10:13]
.LBB0_864:
	s_add_i32 s48, s48, 1
	s_add_i32 s45, s45, 64
	s_cmp_eq_u32 s17, s48
	v_subrev_u32_e32 v196, 64, v196
	s_waitcnt vmcnt(0) lgkmcnt(0)
	s_barrier
	s_cbranch_scc1 .LBB0_870
.LBB0_865:
	s_and_b32 s49, s48, 1
	s_lshl_b32 s4, s45, 14
	s_add_i32 s4, s4, 0x100000
	v_readlane_b32 s5, v254, 60
	s_lshl_b32 s5, s5, 10
	s_cmp_eq_u32 s49, 0
	s_cselect_b32 m0, 0x8400, 0
	s_add_i32 m0, m0, s5
	v_add_u32_e32 v0, s4, v106
	v_add_u32_e32 v4, s4, v107
	global_load_lds_dwordx4 v0, s[24:25]
	s_add_i32 m0, m0, 0x2000
	s_add_i32 s4, s4, 0x40000
	v_add_u32_e32 v1, s4, v106
	v_add_u32_e32 v5, s4, v107
	global_load_lds_dwordx4 v1, s[24:25]
	s_add_i32 m0, m0, 0x2000
	s_add_i32 s4, s4, 0x40000
	v_add_u32_e32 v2, s4, v106
	v_add_u32_e32 v6, s4, v107
	global_load_lds_dwordx4 v2, s[24:25]
	s_add_i32 m0, m0, 0x2000
	s_add_i32 s4, s4, 0x40000
	v_add_u32_e32 v3, s4, v106
	v_add_u32_e32 v7, s4, v107
	global_load_lds_dwordx4 v3, s[24:25]
	s_cmp_eq_u32 s49, 0
	s_cselect_b32 m0, 0x8800, 0
	s_add_i32 m0, m0, s5
	s_add_i32 m0, m0, 0x10800
	s_nop 0
	global_load_lds_dwordx4 v4, s[26:27]
	s_add_i32 m0, m0, 0x2000
	s_nop 0
	global_load_lds_dwordx4 v5, s[26:27]
	s_add_i32 m0, m0, 0x2000
	s_nop 0
	global_load_lds_dwordx4 v6, s[26:27]
	s_add_i32 m0, m0, 0x2000
	s_nop 0
	global_load_lds_dwordx4 v7, s[26:27]
	s_cmp_gt_i32 s45, s16
	s_cbranch_scc1 .LBB0_864
	s_mul_i32 s4, s49, 0x8400
	v_add_u32_e32 v8, s4, v195
	v_xor_b32_e32 v246, 64, v8
	v_xor_b32_e32 v247, 0x80, v8
	v_xor_b32_e32 v248, 0xc0, v8
	ds_read_b128 v[0:3], v8
	ds_read_b128 v[4:7], v8 offset:8192
	ds_read_b128 v[174:177], v8 offset:16384
	ds_read_b128 v[198:201], v8 offset:24576
	ds_read_b128 v[202:205], v246
	ds_read_b128 v[206:209], v246 offset:8192
	ds_read_b128 v[210:213], v246 offset:16384
	ds_read_b128 v[214:217], v246 offset:24576
	ds_read_b128 v[218:221], v247
	ds_read_b128 v[226:229], v247 offset:8192
	ds_read_b128 v[230:233], v247 offset:16384
	ds_read_b128 v[234:237], v247 offset:24576
	ds_read_b128 v[238:241], v248
	ds_read_b128 v[242:245], v248 offset:8192
	s_add_i32 s4, s45, 63
	s_cmp_le_u32 s4, s9
	s_waitcnt lgkmcnt(13)
	v_mfma_f32_16x16x32_bf16 v[150:153], v[0:3], v[102:105], 0
	ds_read_b128 v[0:3], v248 offset:16384
	s_waitcnt lgkmcnt(13)
	v_mfma_f32_16x16x32_bf16 v[146:149], v[4:7], v[102:105], 0
	ds_read_b128 v[4:7], v248 offset:24576
	s_waitcnt lgkmcnt(13)
	v_mfma_f32_16x16x32_bf16 v[142:145], v[174:177], v[102:105], 0
	ds_read_b128 v[174:177], v8 offset:256
	s_waitcnt lgkmcnt(13)
	v_mfma_f32_16x16x32_bf16 v[138:141], v[198:201], v[102:105], 0
	ds_read_b128 v[198:201], v8 offset:8448
	s_waitcnt lgkmcnt(13)
	v_mfma_f32_16x16x32_bf16 v[150:153], v[202:205], v[98:101], v[150:153]
	ds_read_b128 v[202:205], v8 offset:16640
	s_waitcnt lgkmcnt(13)
	v_mfma_f32_16x16x32_bf16 v[146:149], v[206:209], v[98:101], v[146:149]
	ds_read_b128 v[206:209], v8 offset:24832
	s_waitcnt lgkmcnt(13)
	v_mfma_f32_16x16x32_bf16 v[142:145], v[210:213], v[98:101], v[142:145]
	ds_read_b128 v[210:213], v246 offset:256
	s_waitcnt lgkmcnt(13)
	v_mfma_f32_16x16x32_bf16 v[138:141], v[214:217], v[98:101], v[138:141]
	ds_read_b128 v[214:217], v246 offset:8448
	s_waitcnt lgkmcnt(13)
	v_mfma_f32_16x16x32_bf16 v[150:153], v[218:221], v[94:97], v[150:153]
	ds_read_b128 v[218:221], v246 offset:16640
	s_waitcnt lgkmcnt(13)
	v_mfma_f32_16x16x32_bf16 v[146:149], v[226:229], v[94:97], v[146:149]
	ds_read_b128 v[226:229], v246 offset:24832
	s_waitcnt lgkmcnt(13)
	v_mfma_f32_16x16x32_bf16 v[142:145], v[230:233], v[94:97], v[142:145]
	ds_read_b128 v[230:233], v247 offset:256
	s_waitcnt lgkmcnt(13)
	v_mfma_f32_16x16x32_bf16 v[138:141], v[234:237], v[94:97], v[138:141]
	ds_read_b128 v[234:237], v247 offset:8448
	s_waitcnt lgkmcnt(13)
	v_mfma_f32_16x16x32_bf16 v[150:153], v[238:241], v[90:93], v[150:153]
	ds_read_b128 v[238:241], v247 offset:16640
	s_waitcnt lgkmcnt(13)
	v_mfma_f32_16x16x32_bf16 v[146:149], v[242:245], v[90:93], v[146:149]
	ds_read_b128 v[242:245], v247 offset:24832
	s_waitcnt lgkmcnt(13)
	v_mfma_f32_16x16x32_bf16 v[142:145], v[0:3], v[90:93], v[142:145]
	ds_read_b128 v[0:3], v248 offset:256
	s_waitcnt lgkmcnt(13)
	v_mfma_f32_16x16x32_bf16 v[138:141], v[4:7], v[90:93], v[138:141]
	ds_read_b128 v[4:7], v248 offset:8448
	s_waitcnt lgkmcnt(13)
	v_mfma_f32_16x16x32_bf16 v[150:153], v[174:177], v[86:89], v[150:153]
	ds_read_b128 v[174:177], v248 offset:16640
	s_waitcnt lgkmcnt(13)
	v_mfma_f32_16x16x32_bf16 v[146:149], v[198:201], v[86:89], v[146:149]
	ds_read_b128 v[198:201], v248 offset:24832
	s_waitcnt lgkmcnt(13)
	v_mfma_f32_16x16x32_bf16 v[142:145], v[202:205], v[86:89], v[142:145]
	s_waitcnt lgkmcnt(12)
	v_mfma_f32_16x16x32_bf16 v[138:141], v[206:209], v[86:89], v[138:141]
	s_waitcnt lgkmcnt(11)
	v_mfma_f32_16x16x32_bf16 v[150:153], v[210:213], v[82:85], v[150:153]
	s_waitcnt lgkmcnt(10)
	v_mfma_f32_16x16x32_bf16 v[146:149], v[214:217], v[82:85], v[146:149]
	s_waitcnt lgkmcnt(9)
	v_mfma_f32_16x16x32_bf16 v[142:145], v[218:221], v[82:85], v[142:145]
	s_waitcnt lgkmcnt(8)
	v_mfma_f32_16x16x32_bf16 v[138:141], v[226:229], v[82:85], v[138:141]
	s_waitcnt lgkmcnt(7)
	v_mfma_f32_16x16x32_bf16 v[150:153], v[230:233], v[78:81], v[150:153]
	s_waitcnt lgkmcnt(6)
	v_mfma_f32_16x16x32_bf16 v[146:149], v[234:237], v[78:81], v[146:149]
	s_waitcnt lgkmcnt(5)
	v_mfma_f32_16x16x32_bf16 v[142:145], v[238:241], v[78:81], v[142:145]
	s_waitcnt lgkmcnt(4)
	v_mfma_f32_16x16x32_bf16 v[138:141], v[242:245], v[78:81], v[138:141]
	s_waitcnt lgkmcnt(3)
	v_mfma_f32_16x16x32_bf16 v[150:153], v[0:3], v[74:77], v[150:153]
	s_waitcnt lgkmcnt(2)
	v_mfma_f32_16x16x32_bf16 v[146:149], v[4:7], v[74:77], v[146:149]
	s_waitcnt lgkmcnt(1)
	v_mfma_f32_16x16x32_bf16 v[142:145], v[174:177], v[74:77], v[142:145]
	s_waitcnt lgkmcnt(0)
	v_mfma_f32_16x16x32_bf16 v[138:141], v[198:201], v[74:77], v[138:141]
	s_mov_b64 s[4:5], -1
	s_cbranch_scc0 .LBB0_868
	v_cvt_f32_i32_e32 v0, v196
	s_mov_b64 s[4:5], 0
	v_mul_f32_e32 v0, v178, v0
	v_exp_f32_e32 v8, v0
	s_nop 0
	v_mul_f32_e32 v0, s40, v8
	v_pk_mul_f32 v[2:3], s[40:41], v[0:1] op_sel_hi:[1,0]
	v_pk_mul_f32 v[0:1], s[42:43], v[0:1] op_sel_hi:[1,0]
	v_pk_mul_f32 v[2:3], v[2:3], v[150:151]
	v_pk_mul_f32 v[4:5], v[0:1], v[152:153]
	v_cvt_pk_bf16_f32 v0, v2, v3
	v_mul_f32_e32 v2, s44, v8
	v_cvt_pk_bf16_f32 v1, v4, v5
	v_pk_mul_f32 v[4:5], s[40:41], v[2:3] op_sel_hi:[1,0]
	v_pk_mul_f32 v[2:3], s[42:43], v[2:3] op_sel_hi:[1,0]
	v_pk_mul_f32 v[4:5], v[4:5], v[146:147]
	v_pk_mul_f32 v[6:7], v[2:3], v[148:149]
	v_cvt_pk_bf16_f32 v2, v4, v5
	v_mul_f32_e32 v4, s37, v8
	v_cvt_pk_bf16_f32 v3, v6, v7
	v_pk_mul_f32 v[6:7], s[40:41], v[4:5] op_sel_hi:[1,0]
	v_pk_mul_f32 v[4:5], s[42:43], v[4:5] op_sel_hi:[1,0]
	v_pk_mul_f32 v[6:7], v[6:7], v[142:143]
	v_pk_mul_f32 v[154:155], v[4:5], v[144:145]
	v_cvt_pk_bf16_f32 v4, v6, v7
	v_mul_f32_e32 v6, s36, v8
	v_cvt_pk_bf16_f32 v5, v154, v155
	v_pk_mul_f32 v[154:155], s[40:41], v[6:7] op_sel_hi:[1,0]
	v_pk_mul_f32 v[6:7], s[42:43], v[6:7] op_sel_hi:[1,0]
	v_pk_mul_f32 v[174:175], v[154:155], v[138:139]
	v_pk_mul_f32 v[176:177], v[6:7], v[140:141]
